# NORM row loop: all 8 row loads issued at the loop top (late loads renamed to fresh registers)
# baseline (speedup 1.0000x reference)
; __device__ __forceinline__ void norm_phase(const Params& p, int layer) {
;     ...
;         for (int rr = 0; rr < RPW; rr += 2) {
;             const int row = r0 + rr;
;             const f32x4* xa = (const f32x4*)(src + (size_t)row * DM) + lane; const f32x4* xb = xa + DM / 4;
;             f32x4 va[4], vb[4]; float sa = 0.f, sb = 0.f;
; #pragma unroll
;             for (int j = 0; j < 4; ++j) { va[j] = __builtin_nontemporal_load(xa + 64 * j); vb[j] = __builtin_nontemporal_load(xb + 64 * j); }
; #pragma unroll
;             for (int j = 0; j < 4; ++j) { sa += (va[j][0] * va[j][0] + va[j][1] * va[j][1]) + (va[j][2] * va[j][2] + va[j][3] * va[j][3]); sb += (vb[j][0] * vb[j][0] + vb[j][1] * vb[j][1]) + (vb[j][2] * vb[j][2] + vb[j][3] * vb[j][3]); }
;             const float ra = rsqrtf(wave_sum(sa, x32a) * (1.0f / DM) + 1e-6f), rb = rsqrtf(wave_sum(sb, x32a) * (1.0f / DM) + 1e-6f);
.LBB0_415:
	global_load_dwordx4 v[56:59], v[54:55], off offset:-4096 nt
	global_load_dwordx4 v[60:63], v[54:55], off nt
	global_load_dwordx4 v[64:67], v[54:55], off offset:-3072 nt
	global_load_dwordx4 v[70:73], v[54:55], off offset:1024 nt
	global_load_dwordx4 v[102:105], v[54:55], off offset:-2048 nt
	global_load_dwordx4 v[106:109], v[54:55], off offset:-1024 nt
	global_load_dwordx4 v[110:113], v[54:55], off offset:2048 nt
	global_load_dwordx4 v[114:117], v[54:55], off offset:3072 nt
	s_waitcnt vmcnt(7)
	v_pk_mul_f32 v[68:69], v[58:59], v[58:59]
	v_pk_mul_f32 v[74:75], v[56:57], v[56:57]
	s_waitcnt vmcnt(6)
	v_pk_mul_f32 v[76:77], v[62:63], v[62:63]
	v_pk_mov_b32 v[78:79], v[74:75], v[68:69] op_sel:[1,0]
	v_mov_b32_e32 v75, v69
	v_pk_mul_f32 v[68:69], v[60:61], v[60:61]
	s_waitcnt vmcnt(5)
	v_pk_mul_f32 v[82:83], v[64:65], v[64:65]
	v_pk_mov_b32 v[80:81], v[68:69], v[76:77] op_sel:[1,0]
	v_mov_b32_e32 v69, v77
	v_pk_mul_f32 v[76:77], v[66:67], v[66:67]
	s_waitcnt vmcnt(4)
	v_pk_mul_f32 v[86:87], v[70:71], v[70:71]
	v_pk_mov_b32 v[84:85], v[82:83], v[76:77] op_sel:[1,0]
	v_mov_b32_e32 v83, v77
	v_pk_mul_f32 v[76:77], v[72:73], v[72:73]
	v_pk_add_f32 v[90:91], v[78:79], v[74:75]
	v_pk_mov_b32 v[88:89], v[86:87], v[76:77] op_sel:[1,0]
	v_mov_b32_e32 v87, v77
	v_pk_add_f32 v[68:69], v[80:81], v[68:69]
	v_pk_add_f32 v[92:93], v[84:85], v[82:83]
	v_pk_add_f32 v[94:95], v[88:89], v[86:87]
	v_pk_add_f32 v[90:91], v[90:91], v[90:91] op_sel:[0,1] op_sel_hi:[1,0]
	v_pk_add_f32 v[92:93], v[92:93], v[92:93] op_sel:[0,1] op_sel_hi:[1,0]
	v_pk_add_f32 v[68:69], v[68:69], v[68:69] op_sel:[0,1] op_sel_hi:[1,0]
	s_waitcnt vmcnt(3)
	v_mul_f32_e32 v82, v103, v103
	v_mul_f32_e32 v84, v105, v105
	v_pk_fma_f32 v[82:83], v[102:103], v[102:103], v[82:83] op_sel_hi:[1,1,0]
	v_pk_fma_f32 v[84:85], v[104:105], v[104:105], v[84:85] op_sel_hi:[1,1,0]
	s_waitcnt vmcnt(2)
	v_mul_f32_e32 v83, v108, v108
	v_mul_f32_e32 v85, v109, v109
	v_pk_add_f32 v[96:97], v[82:83], v[84:85]
	v_mul_f32_e32 v91, v106, v106
	v_mul_f32_e32 v93, v107, v107
	v_pk_add_f32 v[90:91], v[90:91], v[92:93]
	v_pk_add_f32 v[92:93], v[94:95], v[94:95] op_sel:[0,1] op_sel_hi:[1,0]
	v_pk_add_f32 v[90:91], v[90:91], v[96:97]
	v_lshl_add_u64 v[54:55], v[54:55], 0, s[6:7]
	s_waitcnt vmcnt(1)
	v_mul_f32_e32 v98, v111, v111
	v_mul_f32_e32 v100, v113, v113
	v_pk_fma_f32 v[98:99], v[110:111], v[110:111], v[98:99] op_sel_hi:[1,1,0]
	v_pk_fma_f32 v[100:101], v[112:113], v[112:113], v[100:101] op_sel_hi:[1,1,0]
	s_waitcnt vmcnt(0)
	v_mul_f32_e32 v99, v116, v116
	v_mul_f32_e32 v101, v117, v117
	v_mul_f32_e32 v69, v114, v114
	v_mul_f32_e32 v93, v115, v115
	v_pk_add_f32 v[98:99], v[98:99], v[100:101]
	v_pk_add_f32 v[68:69], v[68:69], v[92:93]
	v_mov_b32_e32 v93, v90
	v_pk_add_f32 v[68:69], v[68:69], v[98:99]
	s_nop 0
	v_mov_b32_e32 v92, v68
	v_mov_b32_e32 v90, v69
	v_pk_add_f32 v[68:69], v[92:93], v[90:91]
	ds_swizzle_b32 v91, v69 offset:swizzle(SWAP,1)
	ds_swizzle_b32 v90, v68 offset:swizzle(SWAP,1)
	s_waitcnt lgkmcnt(0)
	v_pk_add_f32 v[68:69], v[68:69], v[90:91]
	ds_swizzle_b32 v91, v69 offset:swizzle(SWAP,2)
	ds_swizzle_b32 v90, v68 offset:swizzle(SWAP,2)
	s_waitcnt lgkmcnt(0)
	v_pk_add_f32 v[68:69], v[68:69], v[90:91]
	ds_swizzle_b32 v91, v69 offset:swizzle(SWAP,4)
	ds_swizzle_b32 v90, v68 offset:swizzle(SWAP,4)
	s_waitcnt lgkmcnt(0)
	v_pk_add_f32 v[68:69], v[68:69], v[90:91]
	ds_swizzle_b32 v91, v69 offset:swizzle(SWAP,8)
	ds_swizzle_b32 v90, v68 offset:swizzle(SWAP,8)
	s_waitcnt lgkmcnt(0)
	v_pk_add_f32 v[68:69], v[68:69], v[90:91]
	ds_swizzle_b32 v91, v69 offset:swizzle(SWAP,16)
	ds_swizzle_b32 v90, v68 offset:swizzle(SWAP,16)
	s_waitcnt lgkmcnt(0)
	v_pk_add_f32 v[68:69], v[68:69], v[90:91]
	ds_bpermute_b32 v91, v1, v69
	ds_bpermute_b32 v90, v1, v68
	s_waitcnt lgkmcnt(0)
; __device__ __forceinline__ unsigned pk_bf16(float lo, float hi) { const f32x2 v = {lo, hi}; const bf16v2 b = __builtin_convertvector(v, bf16v2); return __builtin_bit_cast(unsigned, b); }
; __device__ __forceinline__ void norm_phase(const Params& p, int layer) {
;     ...
;             const float ra = rsqrtf(wave_sum(sa, x32a) * (1.0f / DM) + 1e-6f), rb = rsqrtf(wave_sum(sb, x32a) * (1.0f / DM) + 1e-6f);
; #pragma unroll
;             for (int j = 0; j < 4; ++j) { const int col = 4 * lane + 256 * j;
;                 const f32x4 ya = (va[j] * ra) * gs[j] + sh[j], yb = (vb[j] * rb) * gs[j] + sh[j];
;                 u32x2 wa, wb; wa.x = pk_bf16(ya[0], ya[1]); wa.y = pk_bf16(ya[2], ya[3]); wb.x = pk_bf16(yb[0], yb[1]); wb.y = pk_bf16(yb[2], yb[3]);
;                 *(u32x2*)(H + (size_t)row * DM + col) = wa; *(u32x2*)(H + (size_t)(row + 1) * DM + col) = wb; }
	v_pk_add_f32 v[68:69], v[68:69], v[90:91]
	s_nop 0
	v_pk_fma_f32 v[90:91], v[68:69], s[8:9], v[206:207] op_sel_hi:[1,0,0]
	s_nop 0
	v_mul_f32_e32 v19, 0x4b800000, v91
	v_cmp_gt_f32_e32 vcc, s82, v91
	s_nop 1
	v_cndmask_b32_e32 v19, v91, v19, vcc
	v_rsq_f32_e32 v19, v19
	s_nop 0
	v_mul_f32_e32 v29, 0x45800000, v19
	v_cndmask_b32_e32 v68, v19, v29, vcc
	v_mul_f32_e32 v19, 0x4b800000, v90
	v_cmp_gt_f32_e32 vcc, s82, v90
	v_pk_mul_f32 v[56:57], v[56:57], v[68:69] op_sel_hi:[1,0]
	v_pk_mul_f32 v[58:59], v[58:59], v[68:69] op_sel_hi:[1,0]
	v_cndmask_b32_e32 v19, v90, v19, vcc
	v_rsq_f32_e32 v19, v19
	v_pk_mul_f32 v[94:95], v[102:103], v[68:69] op_sel_hi:[1,0]
	v_pk_fma_f32 v[58:59], v[36:37], v[58:59], v[4:5]
	v_pk_fma_f32 v[56:57], v[38:39], v[56:57], v[2:3]
	v_mul_f32_e32 v29, 0x45800000, v19
	v_cndmask_b32_e32 v74, v19, v29, vcc
	v_pk_mul_f32 v[60:61], v[60:61], v[74:75] op_sel_hi:[1,0]
	v_pk_mul_f32 v[62:63], v[62:63], v[74:75] op_sel_hi:[1,0]
	v_pk_mul_f32 v[64:65], v[64:65], v[68:69] op_sel_hi:[1,0]
	v_pk_mul_f32 v[92:93], v[66:67], v[68:69] op_sel_hi:[1,0]
	v_cvt_pk_bf16_f32 v56, v56, v57
	v_cvt_pk_bf16_f32 v57, v58, v59
	v_pk_fma_f32 v[62:63], v[36:37], v[62:63], v[4:5]
	v_pk_fma_f32 v[58:59], v[38:39], v[60:61], v[2:3]
	v_pk_mul_f32 v[96:97], v[104:105], v[68:69] op_sel_hi:[1,0]
	v_pk_mul_f32 v[66:67], v[106:107], v[68:69] op_sel_hi:[1,0]
	v_pk_mul_f32 v[68:69], v[108:109], v[68:69] op_sel_hi:[1,0]
	v_pk_mul_f32 v[78:79], v[70:71], v[74:75] op_sel_hi:[1,0]
	v_pk_mul_f32 v[80:81], v[72:73], v[74:75] op_sel_hi:[1,0]
	v_cvt_pk_bf16_f32 v58, v58, v59
	v_cvt_pk_bf16_f32 v59, v62, v63
	v_pk_fma_f32 v[62:63], v[40:41], v[92:93], v[12:13]
	v_pk_fma_f32 v[60:61], v[42:43], v[64:65], v[10:11]
	v_pk_fma_f32 v[64:65], v[40:41], v[80:81], v[12:13]
	v_cvt_pk_bf16_f32 v60, v60, v61
	v_cvt_pk_bf16_f32 v61, v62, v63
	v_pk_fma_f32 v[62:63], v[42:43], v[78:79], v[10:11]
	v_pk_fma_f32 v[78:79], v[44:45], v[96:97], v[16:17]
	v_cvt_pk_bf16_f32 v62, v62, v63
	v_cvt_pk_bf16_f32 v63, v64, v65
	v_pk_fma_f32 v[64:65], v[46:47], v[94:95], v[14:15]
	v_pk_mul_f32 v[72:73], v[110:111], v[74:75] op_sel_hi:[1,0]
	v_cvt_pk_bf16_f32 v64, v64, v65
	v_cvt_pk_bf16_f32 v65, v78, v79
	v_add3_u32 v78, v18, s4, 3
	v_pk_mul_f32 v[76:77], v[112:113], v[74:75] op_sel_hi:[1,0]
	v_pk_mul_f32 v[70:71], v[114:115], v[74:75] op_sel_hi:[1,0]
	v_pk_mul_f32 v[74:75], v[116:117], v[74:75] op_sel_hi:[1,0]
	v_ashrrev_i32_e32 v79, 31, v78
	s_add_i32 s4, s4, 2
	v_lshlrev_b64 v[78:79], 11, v[78:79]
	v_pk_fma_f32 v[76:77], v[44:45], v[76:77], v[16:17]
	v_pk_fma_f32 v[72:73], v[46:47], v[72:73], v[14:15]
	v_pk_fma_f32 v[68:69], v[48:49], v[68:69], v[8:9]
	v_pk_fma_f32 v[66:67], v[50:51], v[66:67], v[6:7]
	v_pk_fma_f32 v[74:75], v[48:49], v[74:75], v[8:9]
	v_pk_fma_f32 v[70:71], v[50:51], v[70:71], v[6:7]
	s_cmp_gt_u32 s4, 13
	v_lshl_add_u64 v[78:79], v[22:23], 0, v[78:79]
	v_cvt_pk_bf16_f32 v72, v72, v73
	v_cvt_pk_bf16_f32 v73, v76, v77
	v_cvt_pk_bf16_f32 v66, v66, v67
	v_cvt_pk_bf16_f32 v67, v68, v69
	v_cvt_pk_bf16_f32 v68, v70, v71
	v_cvt_pk_bf16_f32 v69, v74, v75
	global_store_dwordx2 v[52:53], v[56:57], off offset:-1024
	global_store_dwordx2 v[78:79], v[58:59], off
	global_store_dwordx2 v[52:53], v[60:61], off offset:-512
	global_store_dwordx2 v[78:79], v[62:63], off offset:512
	global_store_dwordx2 v[52:53], v[64:65], off
	global_store_dwordx2 v[78:79], v[72:73], off offset:1024
	global_store_dwordx2 v[52:53], v[66:67], off offset:512
	global_store_dwordx2 v[78:79], v[68:69], off offset:1536
	v_lshl_add_u64 v[52:53], v[52:53], 0, s[98:99]
	s_cbranch_scc0 .LBB0_415
	v_readlane_b32 s4, v254, 62
	v_readlane_b32 s5, v254, 63
	s_nop 0
	v_add_u32_e32 v18, s4, v18
	v_readlane_b32 s4, v254, 51
	v_readlane_b32 s5, v254, 52
	v_cmp_lt_i32_e32 vcc, s2, v18
	s_or_b64 s[40:41], vcc, s[40:41]
	v_lshl_add_u64 v[24:25], v[24:25], 0, s[4:5]
	v_readlane_b32 s4, v255, 0
	v_readlane_b32 s5, v255, 1
	s_nop 1
	v_lshl_add_u64 v[26:27], v[26:27], 0, s[4:5]
	s_andn2_b64 exec, exec, s[40:41]
	s_cbranch_execnz .LBB0_414
